# conv phase: no raised priority for waves 4-7 (on the flips-deleted + side_gemm1 coalesced base)
# speedup vs baseline: 1.0039x; 1.0039x over previous
; __device__ __forceinline__ void phase_conv(const Params& P, int seg) {
;     ...
;     if (__builtin_amdgcn_readfirstlane(threadIdx.x) >= 256) __builtin_amdgcn_s_setprio(1);
.LBB0_173:
	s_or_b64 exec, exec, s[0:1]
	v_readfirstlane_b32 s0, v172
	s_mov_b64 s[42:43], s[80:81]
	s_cmpk_gt_i32 s0, 0xff
	s_waitcnt lgkmcnt(0)
	s_barrier
	s_cbranch_scc0 .LBB0_175
	s_setprio 0
